# v42: v39 + non-temporal hint on the NSA per-item query-tile loads (read-once stream)
# speedup vs baseline: 1.0048x; 1.0048x over previous
.LBB0_1221:
	s_or_b64 exec, exec, s[4:5]
	v_readfirstlane_b32 s0, v1
	s_cmpk_gt_i32 s0, 0x7ff
	s_mov_b64 s[4:5], -1
	s_cbranch_scc1 .LBB0_1216
	s_and_b32 s1, s0, -16
	s_and_b32 s25, s0, 15
	s_sub_i32 s1, s25, s1
	s_addk_i32 s1, 0x7f0
	v_mov_b32_e32 v2, v166
	s_and_b32 s4, s1, 0x7ffffff0
	v_and_b32_e32 v1, 15, v2
	s_and_b32 s24, s0, 1
	s_lshl_b32 s0, s0, 10
	v_or_b32_e32 v207, s4, v1
	s_and_b32 s0, s0, 0x3800
	v_writelane_b32 v254, s4, 57
	v_add_u32_e32 v112, s0, v207
	v_mov_b32_e32 v113, v0
	v_readlane_b32 s4, v255, 4
	v_lshlrev_b64 v[110:111], 10, v[112:113]
	v_readlane_b32 s6, v255, 6
	v_readlane_b32 s7, v255, 7
	s_lshl_b32 s74, s24, 9
	v_and_b32_e32 v114, 48, v2
	v_lshl_add_u64 v[4:5], s[6:7], 0, v[110:111]
	v_lshl_add_u64 v[4:5], v[4:5], 0, s[74:75]
	v_mov_b32_e32 v115, v0
	v_lshl_add_u64 v[32:33], v[4:5], 0, v[114:115]
	global_load_dwordx4 v[4:7], v[32:33], off nt
	global_load_dwordx4 v[8:11], v[32:33], off offset:64 nt
	global_load_dwordx4 v[12:15], v[32:33], off offset:128 nt
	global_load_dwordx4 v[16:19], v[32:33], off offset:192 nt
	global_load_dwordx4 v[20:23], v[32:33], off offset:256 nt
	global_load_dwordx4 v[24:27], v[32:33], off offset:320 nt
	global_load_dwordx4 v[28:31], v[32:33], off offset:384 nt
	s_nop 0
	global_load_dwordx4 v[32:35], v[32:33], off offset:448 nt
	v_writelane_b32 v254, s0, 58
	v_and_b32_e32 v113, 63, v2
	s_or_b32 s0, s1, 15
	v_readlane_b32 s5, v255, 5
	v_mad_u32_u24 v3, v113, 36, v172
	s_cmp_lt_u32 s0, 31
	v_lshl_add_u32 v208, v113, 4, v172
	v_add_u32_e32 v36, 0x2000, v3
	s_cselect_b64 s[20:21], -1, 0
	s_cmp_gt_u32 s0, 30
	s_mov_b64 s[4:5], -1
	v_readlane_b32 s8, v255, 8
	v_readlane_b32 s9, v255, 9
	v_readlane_b32 s10, v255, 10
	v_readlane_b32 s11, v255, 11
	v_add_u32_e32 v37, 0x2008, v3
	v_add_u32_e32 v38, 0x2010, v3
	v_add_u32_e32 v39, 0x2018, v3
	ds_write_b32 v3, v175 offset:8224
	ds_write2_b32 v36, v0, v0 offset1:1
	ds_write2_b32 v37, v0, v0 offset1:1
	ds_write2_b32 v38, v0, v0 offset1:1
	ds_write2_b32 v39, v0, v0 offset1:1
	s_waitcnt vmcnt(7)
	ds_write_b128 v208, v[4:7]
	s_waitcnt vmcnt(6)
	ds_write_b128 v208, v[8:11] offset:1024
	s_waitcnt vmcnt(5)
	ds_write_b128 v208, v[12:15] offset:2048
	s_waitcnt vmcnt(4)
	ds_write_b128 v208, v[16:19] offset:3072
	s_waitcnt vmcnt(3)
	ds_write_b128 v208, v[20:23] offset:4096
	s_waitcnt vmcnt(2)
	ds_write_b128 v208, v[24:27] offset:5120
	s_waitcnt vmcnt(1)
	ds_write_b128 v208, v[28:31] offset:6144
	s_waitcnt vmcnt(0)
	ds_write_b128 v208, v[32:35] offset:7168
	s_cbranch_scc1 .LBB0_1224
	s_mov_b64 s[4:5], 0
